# baseline (speedup 1.0000x reference)
; __device__ __forceinline__ int otid() { int t; asm volatile("v_mov_b32 %0, %1" : "=v"(t) : "v"((int)threadIdx.x)); return t; }
; #define SETPTR(IT) { const int mt_ = ITEM_MT(IT), nt_ = ITEM_NT(IT); ga = A + (size_t)(mt_ * AROWS + srow) * lda + (skc ^ fs) * 8; gb = Bt + (size_t)(nt_ * 256 + srow) * ldb + (skc ^ fs) * 8; }
; #define ADV() { ga += 32; gb += 32; ck += 32; if (ck == K) { ck = 0; citem += gridDim.x; const int ci_ = citem < total ? citem : total - 1; SETPTR(ci_) } }
; #define WAITSTEP() { if (a2) WAITV(4); else WAITV(3); }
;     ...
;   const int tid = otid(), lane = tid & 63, wid = tid >> 6, wm = wid >> 2, wn = wid & 3, l15 = lane & 15, quad = lane >> 4;
;   const int srow = tid >> 2, skc = tid & 3;
;   constexpr int AROWS = MI * 32, ABYTES = AROWS * 64, STAGE = ABYTES + 16384;
;   constexpr int GRP = 4;
;   const int fr = (-(l15 >> 2)) & 3, fs = (-(srow >> 2)) & 3;
;   const int aoff = (wm * (MI * 16) + l15) * 64 + (quad ^ fr) * 16, boff = ABYTES + (wn * 64 + l15) * 64 + (quad ^ fr) * 16;
;   const int nk = K >> 5;
;   const bool a2 = (MI != 4);
;   const int a2row = (MI == 6 && tid >= 256) ? 64 : 128, a2lds = (MI == 6 && tid >= 256) ? 4096 : 8192;
;   int citem = item, ck = 0;
;   const u16* ga; const u16* gb;
;     ...
;   SETPTR(citem)
;   GLDS(0) ADV()
;   GLDS(STAGE) ADV()
;   WAITSTEP()
;   __builtin_amdgcn_s_barrier();
;   int scur = 0, snext = 2 * STAGE;
.LBB0_1755:
	v_readlane_b32 s2, v255, 10
	v_readlane_b32 s3, v255, 11
	s_andn2_b64 vcc, exec, s[2:3]
	s_cbranch_vccnz .LBB0_1764
	v_mov_b32 v12, v200
	v_readlane_b32 s2, v255, 13
	v_ashrrev_i32_e32 v108, 2, v12
	v_lshrrev_b32_e32 v0, 4, v12
	v_sub_u32_e32 v4, 0, v0
	v_add_u32_e32 v0, s2, v108
	v_ashrrev_i32_e32 v3, 31, v0
	v_mad_u64_u32 v[0:1], s[2:3], v0, s86, 0
	v_mov_b32_e32 v2, v1
	v_mad_u64_u32 v[2:3], s[2:3], v3, s86, v[2:3]
	v_mov_b32_e32 v1, v2
	v_xor_b32_e32 v2, v12, v4
	v_lshlrev_b32_e32 v2, 4, v2
	v_readlane_b32 s2, v255, 14
	v_and_b32_e32 v128, 48, v2
	v_lshl_add_u32 v109, v12, 4, 0
	v_add_u32_e32 v2, s2, v108
	v_ashrrev_i32_e32 v5, 31, v2
	v_mad_u64_u32 v[2:3], s[2:3], v2, s86, 0
	v_mov_b32_e32 v4, v3
	v_mad_u64_u32 v[4:5], s[2:3], v5, s86, v[4:5]
	v_readfirstlane_b32 s2, v109
	v_readfirstlane_b32 s100, v109
	s_mov_b32 m0, s2
	s_movk_i32 s2, 0xff
	v_cmp_lt_i32_e32 vcc, s2, v12
	v_mov_b32_e32 v6, 0x2000
	v_mov_b32_e32 v7, 0x1000
	v_cndmask_b32_e32 v110, v6, v7, vcc
	v_lshl_add_u64 v[0:1], v[0:1], 1, s[6:7]
	v_mov_b32_e32 v3, v4
	v_cndmask_b32_e64 v4, 7, 6, vcc
	v_add_u32_e32 v13, v109, v110
	v_readfirstlane_b32 s101, v110
	v_lshl_add_u64 v[0:1], v[0:1], 0, v[128:129]
	v_lshlrev_b64 v[96:97], v4, s[86:87]
	v_readfirstlane_b32 s2, v13
	v_add_u32_e32 v6, 0x3000, v109
	v_lshl_add_u64 v[2:3], v[2:3], 1, s[4:5]
	global_load_lds_dwordx4 v[0:1], off
	v_lshl_add_u64 v[4:5], v[96:97], 1, v[0:1]
	s_mov_b32 m0, s2
	v_readfirstlane_b32 s2, v6
	v_lshl_add_u64 v[2:3], v[2:3], 0, v[128:129]
	global_load_lds_dwordx4 v[4:5], off
	s_mov_b32 m0, s2
	s_lshl_b64 s[2:3], s[86:87], 8
	v_add_u32_e32 v8, 0x5000, v109
	v_lshl_add_u64 v[6:7], v[2:3], 0, s[2:3]
	v_readfirstlane_b32 s2, v8
	v_add_u32_e32 v14, 0x7000, v109
	global_load_lds_dwordx4 v[2:3], off
	s_mov_b32 m0, s2
	v_readfirstlane_b32 s2, v14
	global_load_lds_dwordx4 v[6:7], off
	v_lshl_add_u64 v[10:11], v[0:1], 0, 64
	s_mov_b32 m0, s2
	v_lshl_add_u64 v[4:5], v[4:5], 0, 64
	global_load_lds_dwordx4 v[10:11], off
	v_add_u32_e32 v10, 0x7000, v13
	v_lshl_add_u64 v[8:9], v[2:3], 0, 64
	v_readfirstlane_b32 s2, v10
	s_mov_b32 m0, s2
	s_mov_b64 s[12:13], 0x80
	global_load_lds_dwordx4 v[4:5], off
	v_add_u32_e32 v4, 0xa000, v109
	v_readlane_b32 s63, v255, 12
	v_readfirstlane_b32 s2, v4
	v_lshl_add_u64 v[4:5], v[6:7], 0, 64
	v_add_u32_e32 v6, 0xc000, v109
	s_mov_b32 m0, s2
	v_readfirstlane_b32 s2, v6
	global_load_lds_dwordx4 v[8:9], off
	s_mov_b32 m0, s2
	s_lshr_b32 s9, s86, 5
	global_load_lds_dwordx4 v[4:5], off
	v_lshrrev_b32_e32 v4, 8, v12
	v_mul_i32_i24_e32 v4, 0x60, v4
	v_and_or_b32 v4, v12, 15, v4
	v_lshlrev_b32_e32 v111, 6, v4
	v_lshlrev_b32_e32 v4, 2, v12
	v_and_b32_e32 v4, 48, v4
	v_sub_u32_e32 v4, 0, v4
	s_waitcnt vmcnt(0)
	v_bitop3_b32 v112, v12, 48, v4 bitop3:0x48
	v_lshlrev_b32_e32 v4, 6, v12
	s_lshl_b64 s[2:3], s[86:87], 7
	s_mov_b32 s62, 0
	v_and_b32_e32 v113, 0x33c0, v4
	v_lshl_add_u64 v[104:105], v[2:3], 0, s[12:13]
	v_lshl_add_u64 v[102:103], v[0:1], 0, s[12:13]
	v_lshl_add_u64 v[98:99], s[6:7], 0, v[128:129]
	v_lshl_add_u64 v[100:101], s[4:5], 0, v[128:129]
	s_mov_b32 s74, 64
	s_mov_b32 s6, 0xe000
	s_mov_b32 s7, s63
	s_barrier
	s_branch .LBB0_1758

; #define MFMA(a, b, c) __builtin_amdgcn_mfma_f32_16x16x32_bf16((a), (b), (c), 0, 0, 0)
; #define ADV() { ga += 32; gb += 32; ck += 32; if (ck == K) { ck = 0; citem += gridDim.x; const int ci_ = citem < total ? citem : total - 1; SETPTR(ci_) } }
; #define WAITSTEP() { if (a2) WAITV(4); else WAITV(3); }
;     ...
;     for (int kt = 0; kt < nk; ++kt) {
;       if (VAR != 1) { const char* base = lds + scur; bf16x8 a[MI], b[4];
; #pragma unroll
;         for (int i = 0; i < 4; ++i) b[i] = *(const bf16x8*)(base + boff + i * 1024);
; #pragma unroll
;         for (int i = 0; i < MI; ++i) a[i] = *(const bf16x8*)(base + aoff + i * 1024);
; #pragma unroll
;         for (int i = 0; i < MI; ++i)
; #pragma unroll
;           for (int j = 0; j < 4; ++j) acc[i][j] = MFMA(a[i], b[j], acc[i][j]);
;         if (VAR != 2) GLDS(snext)
;     ...
;         if (MI == 8) {
;           __builtin_amdgcn_sched_group_barrier(0x100, MI + 4, 0);
; #pragma unroll
;           for (int g = 0; g < 4; ++g) { __builtin_amdgcn_sched_group_barrier(0x008, 7, 0); __builtin_amdgcn_sched_group_barrier(0x010, 1, 0); }
;           __builtin_amdgcn_sched_group_barrier(0x008, 4, 0);
;         } else if (MI == 6) {
;           __builtin_amdgcn_sched_group_barrier(0x100, MI + 4, 0);
; #pragma unroll
;           for (int g = 0; g < 4; ++g) { __builtin_amdgcn_sched_group_barrier(0x008, 5, 0); __builtin_amdgcn_sched_group_barrier(0x010, 1, 0); }
;           __builtin_amdgcn_sched_group_barrier(0x008, 4, 0);
;         }
;     ...
;       }
;       ADV()
;       if (VAR == 2) {} else WAITSTEP()
;       __builtin_amdgcn_s_barrier();
;       scur = (scur == 2 * STAGE) ? 0 : scur + STAGE;
;       snext = (snext == 2 * STAGE) ? 0 : snext + STAGE;
.LBB0_1760:
	s_xor_b32 s62, s62, 0xe000
	s_xor_b32 s6, s6, 0xe000
	s_waitcnt vmcnt(0)
	s_add_i32 s4, s4, -2
	s_cmp_eq_u32 s4, 0
	s_barrier
	s_cbranch_scc1 .LBB0_1757
.LBB0_1761:
	s_cmpk_ge_u32 s100, 0x1000
	s_cbranch_scc1 .Lres6_hi
	s_add_i32 s5, s62, 0
	v_add3_u32 v107, s5, v111, v112
	v_add3_u32 v106, s5, v113, v112
	ds_read_b128 v[118:121], v107
	ds_read_b128 v[114:117], v106 offset:12288
	ds_read_b128 v[122:125], v106 offset:13312
	ds_read_b128 v[132:135], v106 offset:14336
	ds_read_b128 v[136:139], v106 offset:15360
	ds_read_b128 v[140:143], v107 offset:1024
	ds_read_b128 v[144:147], v107 offset:2048
	ds_read_b128 v[148:151], v107 offset:3072
	ds_read_b128 v[152:155], v107 offset:4096
	ds_read_b128 v[156:159], v107 offset:5120
	s_add_i32 s5, s6, s100
	s_mov_b32 m0, s5
	v_lshl_add_u64 v[196:197], s[2:3], 1, v[104:105]
	v_lshl_add_u64 v[244:245], v[102:103], 0, 64
	v_lshl_add_u64 v[248:249], v[104:105], 0, 64
	v_lshl_add_u64 v[250:251], v[196:197], 0, 64
	v_lshl_add_u64 v[194:195], v[96:97], 1, v[102:103]
	v_lshl_add_u64 v[246:247], v[194:195], 0, 64
	s_nop 0
	global_load_lds_dwordx4 v[102:103], off
	s_add_i32 m0, s5, s101
	s_nop 0
	global_load_lds_dwordx4 v[194:195], off
	s_add_i32 m0, s5, 0x3000
	s_nop 0
	global_load_lds_dwordx4 v[104:105], off
	s_add_i32 m0, s5, 0x5000
	s_nop 0
	global_load_lds_dwordx4 v[196:197], off
	s_add_i32 m0, s5, 0x7000
	s_nop 0
	global_load_lds_dwordx4 v[244:245], off
	s_add_i32 m0, s5, s101
	s_add_i32 m0, m0, 0x7000
	s_nop 0
	global_load_lds_dwordx4 v[246:247], off
	s_add_i32 m0, s5, 0xa000
	s_nop 0
	global_load_lds_dwordx4 v[248:249], off
	s_add_i32 m0, s5, 0xc000
	s_nop 0
	global_load_lds_dwordx4 v[250:251], off
	s_waitcnt lgkmcnt(8)
	v_mfma_f32_16x16x32_bf16 v[92:95], v[118:121], v[114:117], v[92:95]
	s_waitcnt lgkmcnt(7)
	v_mfma_f32_16x16x32_bf16 v[88:91], v[118:121], v[122:125], v[88:91]
	s_waitcnt lgkmcnt(6)
	v_mfma_f32_16x16x32_bf16 v[84:87], v[118:121], v[132:135], v[84:87]
	s_waitcnt lgkmcnt(5)
	v_mfma_f32_16x16x32_bf16 v[80:83], v[118:121], v[136:139], v[80:83]
	ds_read_b128 v[228:231], v106 offset:40960
	ds_read_b128 v[232:235], v106 offset:41984
	ds_read_b128 v[236:239], v106 offset:43008
	ds_read_b128 v[240:243], v106 offset:44032
	ds_read_b128 v[118:121], v107 offset:28672
	s_waitcnt lgkmcnt(9)
	v_mfma_f32_16x16x32_bf16 v[76:79], v[140:143], v[114:117], v[76:79]
	v_mfma_f32_16x16x32_bf16 v[72:75], v[140:143], v[122:125], v[72:75]
	v_mfma_f32_16x16x32_bf16 v[68:71], v[140:143], v[132:135], v[68:71]
	v_mfma_f32_16x16x32_bf16 v[64:67], v[140:143], v[136:139], v[64:67]
	ds_read_b128 v[140:143], v107 offset:29696
	s_waitcnt lgkmcnt(9)
	v_mfma_f32_16x16x32_bf16 v[60:63], v[144:147], v[114:117], v[60:63]
	v_mfma_f32_16x16x32_bf16 v[56:59], v[144:147], v[122:125], v[56:59]
	v_mfma_f32_16x16x32_bf16 v[52:55], v[144:147], v[132:135], v[52:55]
	v_mfma_f32_16x16x32_bf16 v[48:51], v[144:147], v[136:139], v[48:51]
	ds_read_b128 v[144:147], v107 offset:30720
	s_waitcnt lgkmcnt(9)
	v_mfma_f32_16x16x32_bf16 v[36:39], v[148:151], v[114:117], v[36:39]
	v_mfma_f32_16x16x32_bf16 v[32:35], v[148:151], v[122:125], v[32:35]
	v_mfma_f32_16x16x32_bf16 v[40:43], v[148:151], v[132:135], v[40:43]
	v_mfma_f32_16x16x32_bf16 v[44:47], v[148:151], v[136:139], v[44:47]
	ds_read_b128 v[148:151], v107 offset:31744
	s_waitcnt lgkmcnt(9)
	v_mfma_f32_16x16x32_bf16 v[16:19], v[152:155], v[114:117], v[16:19]
	v_mfma_f32_16x16x32_bf16 v[20:23], v[152:155], v[122:125], v[20:23]
	v_mfma_f32_16x16x32_bf16 v[24:27], v[152:155], v[132:135], v[24:27]
	v_mfma_f32_16x16x32_bf16 v[28:31], v[152:155], v[136:139], v[28:31]
	ds_read_b128 v[152:155], v107 offset:32768
	s_waitcnt lgkmcnt(9)
	v_mfma_f32_16x16x32_bf16 v[0:3], v[156:159], v[114:117], v[0:3]
	v_mfma_f32_16x16x32_bf16 v[4:7], v[156:159], v[122:125], v[4:7]
	v_mfma_f32_16x16x32_bf16 v[8:11], v[156:159], v[132:135], v[8:11]
	v_mfma_f32_16x16x32_bf16 v[12:15], v[156:159], v[136:139], v[12:15]
	ds_read_b128 v[156:159], v107 offset:33792
	s_waitcnt lgkmcnt(5)
	v_mfma_f32_16x16x32_bf16 v[92:95], v[118:121], v[228:231], v[92:95]
	v_mfma_f32_16x16x32_bf16 v[88:91], v[118:121], v[232:235], v[88:91]
	v_mfma_f32_16x16x32_bf16 v[84:87], v[118:121], v[236:239], v[84:87]
	v_mfma_f32_16x16x32_bf16 v[80:83], v[118:121], v[240:243], v[80:83]
	s_waitcnt lgkmcnt(4)
	v_mfma_f32_16x16x32_bf16 v[76:79], v[140:143], v[228:231], v[76:79]
	v_mfma_f32_16x16x32_bf16 v[72:75], v[140:143], v[232:235], v[72:75]
	v_mfma_f32_16x16x32_bf16 v[68:71], v[140:143], v[236:239], v[68:71]
	v_mfma_f32_16x16x32_bf16 v[64:67], v[140:143], v[240:243], v[64:67]
	s_waitcnt lgkmcnt(3)
	v_mfma_f32_16x16x32_bf16 v[60:63], v[144:147], v[228:231], v[60:63]
	v_mfma_f32_16x16x32_bf16 v[56:59], v[144:147], v[232:235], v[56:59]
	v_mfma_f32_16x16x32_bf16 v[52:55], v[144:147], v[236:239], v[52:55]
	v_mfma_f32_16x16x32_bf16 v[48:51], v[144:147], v[240:243], v[48:51]
	s_waitcnt lgkmcnt(2)
	v_mfma_f32_16x16x32_bf16 v[36:39], v[148:151], v[228:231], v[36:39]
	v_mfma_f32_16x16x32_bf16 v[32:35], v[148:151], v[232:235], v[32:35]
	v_mfma_f32_16x16x32_bf16 v[40:43], v[148:151], v[236:239], v[40:43]
	v_mfma_f32_16x16x32_bf16 v[44:47], v[148:151], v[240:243], v[44:47]
	s_waitcnt lgkmcnt(1)
	v_mfma_f32_16x16x32_bf16 v[16:19], v[152:155], v[228:231], v[16:19]
	v_mfma_f32_16x16x32_bf16 v[20:23], v[152:155], v[232:235], v[20:23]
	v_mfma_f32_16x16x32_bf16 v[24:27], v[152:155], v[236:239], v[24:27]
	v_mfma_f32_16x16x32_bf16 v[28:31], v[152:155], v[240:243], v[28:31]
	s_waitcnt lgkmcnt(0)
	v_mfma_f32_16x16x32_bf16 v[0:3], v[156:159], v[228:231], v[0:3]
	v_mfma_f32_16x16x32_bf16 v[4:7], v[156:159], v[232:235], v[4:7]
	v_mfma_f32_16x16x32_bf16 v[8:11], v[156:159], v[236:239], v[8:11]
	v_mfma_f32_16x16x32_bf16 v[12:15], v[156:159], v[240:243], v[12:15]
	s_add_i32 s74, s74, 64
	s_cmp_lg_u32 s74, s86
	s_cbranch_scc0 .LBB0_1759
	s_branch .Lres6_adv
; #define MFMA(a, b, c) __builtin_amdgcn_mfma_f32_16x16x32_bf16((a), (b), (c), 0, 0, 0)
; #define ADV() { ga += 32; gb += 32; ck += 32; if (ck == K) { ck = 0; citem += gridDim.x; const int ci_ = citem < total ? citem : total - 1; SETPTR(ci_) } }
; #define WAITSTEP() { if (a2) WAITV(4); else WAITV(3); }
;     ...
;     for (int kt = 0; kt < nk; ++kt) {
;       if (VAR != 1) { const char* base = lds + scur; bf16x8 a[MI], b[4];
; #pragma unroll
;         for (int i = 0; i < 4; ++i) b[i] = *(const bf16x8*)(base + boff + i * 1024);
; #pragma unroll
;         for (int i = 0; i < MI; ++i) a[i] = *(const bf16x8*)(base + aoff + i * 1024);
; #pragma unroll
;         for (int i = 0; i < MI; ++i)
; #pragma unroll
;           for (int j = 0; j < 4; ++j) acc[i][j] = MFMA(a[i], b[j], acc[i][j]);
;         if (VAR != 2) GLDS(snext)
;     ...
;         if (MI == 8) {
;           __builtin_amdgcn_sched_group_barrier(0x100, MI + 4, 0);
; #pragma unroll
;           for (int g = 0; g < 4; ++g) { __builtin_amdgcn_sched_group_barrier(0x008, 7, 0); __builtin_amdgcn_sched_group_barrier(0x010, 1, 0); }
;           __builtin_amdgcn_sched_group_barrier(0x008, 4, 0);
;         } else if (MI == 6) {
;           __builtin_amdgcn_sched_group_barrier(0x100, MI + 4, 0);
; #pragma unroll
;           for (int g = 0; g < 4; ++g) { __builtin_amdgcn_sched_group_barrier(0x008, 5, 0); __builtin_amdgcn_sched_group_barrier(0x010, 1, 0); }
;           __builtin_amdgcn_sched_group_barrier(0x008, 4, 0);
;         }
;     ...
;       }
;       ADV()
;       if (VAR == 2) {} else WAITSTEP()
;       __builtin_amdgcn_s_barrier();
;       scur = (scur == 2 * STAGE) ? 0 : scur + STAGE;
;       snext = (snext == 2 * STAGE) ? 0 : snext + STAGE;
.Lres6_hi:
	s_add_i32 s5, s62, 0
	v_add3_u32 v107, s5, v111, v112
	v_add3_u32 v106, s5, v113, v112
	ds_read_b128 v[118:121], v107
	ds_read_b128 v[114:117], v106 offset:12288
	ds_read_b128 v[122:125], v106 offset:13312
	ds_read_b128 v[132:135], v106 offset:14336
	ds_read_b128 v[136:139], v106 offset:15360
	ds_read_b128 v[140:143], v107 offset:1024
	ds_read_b128 v[144:147], v107 offset:2048
	ds_read_b128 v[148:151], v107 offset:3072
	ds_read_b128 v[152:155], v107 offset:4096
	ds_read_b128 v[156:159], v107 offset:5120
	s_waitcnt lgkmcnt(8)
	v_mfma_f32_16x16x32_bf16 v[92:95], v[118:121], v[114:117], v[92:95]
	s_waitcnt lgkmcnt(7)
	v_mfma_f32_16x16x32_bf16 v[88:91], v[118:121], v[122:125], v[88:91]
	s_add_i32 s5, s6, s100
	s_mov_b32 m0, s5
	v_lshl_add_u64 v[196:197], s[2:3], 1, v[104:105]
	v_lshl_add_u64 v[244:245], v[102:103], 0, 64
	v_lshl_add_u64 v[248:249], v[104:105], 0, 64
	v_lshl_add_u64 v[250:251], v[196:197], 0, 64
	s_waitcnt lgkmcnt(6)
	v_mfma_f32_16x16x32_bf16 v[84:87], v[118:121], v[132:135], v[84:87]
	s_waitcnt lgkmcnt(5)
	v_mfma_f32_16x16x32_bf16 v[80:83], v[118:121], v[136:139], v[80:83]
	ds_read_b128 v[228:231], v106 offset:40960
	ds_read_b128 v[232:235], v106 offset:41984
	ds_read_b128 v[236:239], v106 offset:43008
	ds_read_b128 v[240:243], v106 offset:44032
	ds_read_b128 v[118:121], v107 offset:28672
	s_waitcnt lgkmcnt(9)
	v_mfma_f32_16x16x32_bf16 v[76:79], v[140:143], v[114:117], v[76:79]
	v_mfma_f32_16x16x32_bf16 v[72:75], v[140:143], v[122:125], v[72:75]
	global_load_lds_dwordx4 v[102:103], off
	s_add_i32 m0, s5, 0x3000
	v_mfma_f32_16x16x32_bf16 v[68:71], v[140:143], v[132:135], v[68:71]
	v_mfma_f32_16x16x32_bf16 v[64:67], v[140:143], v[136:139], v[64:67]
	ds_read_b128 v[140:143], v107 offset:29696
	s_waitcnt lgkmcnt(9)
	v_mfma_f32_16x16x32_bf16 v[60:63], v[144:147], v[114:117], v[60:63]
	v_mfma_f32_16x16x32_bf16 v[56:59], v[144:147], v[122:125], v[56:59]
	global_load_lds_dwordx4 v[104:105], off
	s_add_i32 m0, s5, 0x5000
	v_mfma_f32_16x16x32_bf16 v[52:55], v[144:147], v[132:135], v[52:55]
	v_mfma_f32_16x16x32_bf16 v[48:51], v[144:147], v[136:139], v[48:51]
	ds_read_b128 v[144:147], v107 offset:30720
	s_waitcnt lgkmcnt(9)
	v_mfma_f32_16x16x32_bf16 v[36:39], v[148:151], v[114:117], v[36:39]
	v_mfma_f32_16x16x32_bf16 v[32:35], v[148:151], v[122:125], v[32:35]
	global_load_lds_dwordx4 v[196:197], off
	s_add_i32 m0, s5, 0x7000
	v_mfma_f32_16x16x32_bf16 v[40:43], v[148:151], v[132:135], v[40:43]
	v_mfma_f32_16x16x32_bf16 v[44:47], v[148:151], v[136:139], v[44:47]
	ds_read_b128 v[148:151], v107 offset:31744
	s_waitcnt lgkmcnt(9)
	v_mfma_f32_16x16x32_bf16 v[16:19], v[152:155], v[114:117], v[16:19]
	v_mfma_f32_16x16x32_bf16 v[20:23], v[152:155], v[122:125], v[20:23]
	global_load_lds_dwordx4 v[244:245], off
	s_add_i32 m0, s5, 0xa000
	v_mfma_f32_16x16x32_bf16 v[24:27], v[152:155], v[132:135], v[24:27]
	v_mfma_f32_16x16x32_bf16 v[28:31], v[152:155], v[136:139], v[28:31]
	ds_read_b128 v[152:155], v107 offset:32768
	s_waitcnt lgkmcnt(9)
	v_mfma_f32_16x16x32_bf16 v[0:3], v[156:159], v[114:117], v[0:3]
	v_mfma_f32_16x16x32_bf16 v[4:7], v[156:159], v[122:125], v[4:7]
	global_load_lds_dwordx4 v[248:249], off
	s_add_i32 m0, s5, 0xc000
	v_mfma_f32_16x16x32_bf16 v[8:11], v[156:159], v[132:135], v[8:11]
	v_mfma_f32_16x16x32_bf16 v[12:15], v[156:159], v[136:139], v[12:15]
	ds_read_b128 v[156:159], v107 offset:33792
	s_waitcnt lgkmcnt(5)
	v_mfma_f32_16x16x32_bf16 v[92:95], v[118:121], v[228:231], v[92:95]
	v_mfma_f32_16x16x32_bf16 v[88:91], v[118:121], v[232:235], v[88:91]
	global_load_lds_dwordx4 v[250:251], off
	v_mfma_f32_16x16x32_bf16 v[84:87], v[118:121], v[236:239], v[84:87]
	v_mfma_f32_16x16x32_bf16 v[80:83], v[118:121], v[240:243], v[80:83]
	s_waitcnt lgkmcnt(4)
	v_mfma_f32_16x16x32_bf16 v[76:79], v[140:143], v[228:231], v[76:79]
	v_mfma_f32_16x16x32_bf16 v[72:75], v[140:143], v[232:235], v[72:75]
	v_mfma_f32_16x16x32_bf16 v[68:71], v[140:143], v[236:239], v[68:71]
	v_mfma_f32_16x16x32_bf16 v[64:67], v[140:143], v[240:243], v[64:67]
	s_waitcnt lgkmcnt(3)
	v_mfma_f32_16x16x32_bf16 v[60:63], v[144:147], v[228:231], v[60:63]
	v_mfma_f32_16x16x32_bf16 v[56:59], v[144:147], v[232:235], v[56:59]
	v_mfma_f32_16x16x32_bf16 v[52:55], v[144:147], v[236:239], v[52:55]
	v_mfma_f32_16x16x32_bf16 v[48:51], v[144:147], v[240:243], v[48:51]
	s_waitcnt lgkmcnt(2)
	v_mfma_f32_16x16x32_bf16 v[36:39], v[148:151], v[228:231], v[36:39]
	v_mfma_f32_16x16x32_bf16 v[32:35], v[148:151], v[232:235], v[32:35]
	v_mfma_f32_16x16x32_bf16 v[40:43], v[148:151], v[236:239], v[40:43]
	v_mfma_f32_16x16x32_bf16 v[44:47], v[148:151], v[240:243], v[44:47]
	s_waitcnt lgkmcnt(1)
	v_mfma_f32_16x16x32_bf16 v[16:19], v[152:155], v[228:231], v[16:19]
	v_mfma_f32_16x16x32_bf16 v[20:23], v[152:155], v[232:235], v[20:23]
	v_mfma_f32_16x16x32_bf16 v[24:27], v[152:155], v[236:239], v[24:27]
	v_mfma_f32_16x16x32_bf16 v[28:31], v[152:155], v[240:243], v[28:31]
	s_waitcnt lgkmcnt(0)
	v_mfma_f32_16x16x32_bf16 v[0:3], v[156:159], v[228:231], v[0:3]
	v_mfma_f32_16x16x32_bf16 v[4:7], v[156:159], v[232:235], v[4:7]
	v_mfma_f32_16x16x32_bf16 v[8:11], v[156:159], v[236:239], v[8:11]
	v_mfma_f32_16x16x32_bf16 v[12:15], v[156:159], v[240:243], v[12:15]
	s_add_i32 s74, s74, 64
	s_cmp_lg_u32 s74, s86
	s_cbranch_scc0 .LBB0_1759
.Lres6_adv:
	v_lshl_add_u64 v[102:103], v[102:103], 0, 64
	v_lshl_add_u64 v[104:105], v[104:105], 0, 64
	v_lshl_add_u64 v[102:103], v[102:103], 0, 64
	v_lshl_add_u64 v[104:105], v[104:105], 0, 64
	s_branch .LBB0_1760
